# batch the MoE expert-list row loads: GU unit head (4 loads, one wait) and hand-written DN epilogue (8 loads, one wait, 16 stores)
# speedup vs baseline: 1.0134x; 1.0134x over previous
;     __device__ __forceinline__ bool next(int i, Unit& u) const { u.e = 0; u.aux = 0; u.cnt = 256; return o.next(i, u.pm, u.pn); }
;     __device__ __forceinline__ unsigned arow(const Unit& u, int r) const { return (unsigned)(u.pm * 256 + r); }
; #define G_VOA(dst, u) do { _Pragma("unroll") for (int h = 0; h < 2; ++h) _Pragma("unroll") for (int i = 0; i < 2; ++i) dst[h][i] = (S.arow(u, h * HALF + R0 + 64 * i) * (unsigned)K + (unsigned)C0) * 2u; } while (0)
;     __device__ __forceinline__ unsigned arow(const Unit& u, int r) const {
;         if (!gatherA) return (unsigned)(u.pm * 256 + r);
;         if (!moe) return (unsigned)(u.aux + r);
;         return (r < u.cnt) ? ((unsigned)list[(size_t)u.e * M + u.aux + r] >> 1) : 0u;
;     }
;     ...
;         const bool has_next = S.next(ui + 1, nxt);
;         const char* nB = cB;
;         { unsigned nvo[2][2];
;           if (has_next) { G_VOA(nvo, nxt); nB = (const char*)S.bbase(nxt) + (size_t)nxt.pn * tstep; }
.LBB0_977:
	v_cndmask_b32_e64 v2, 0, 1, s[42:43]
	v_cmp_ne_u32_e64 s[40:41], 1, v2
	s_andn2_b64 vcc, exec, s[42:43]
	v_mov_b64_e32 v[176:177], v[6:7]
	v_mov_b32_e32 v2, v34
	v_mov_b32_e32 v3, v35
	v_mov_b32_e32 v4, v36
	v_mov_b32_e32 v5, v37
	s_cbranch_vccnz .LBB0_1003
	s_ashr_i32 s55, s54, 31
	s_ashr_i32 s59, s58, 31
	s_lshl_b64 s[12:13], s[54:55], 18
	s_add_u32 s7, s61, s12
	s_addc_u32 s24, s62, s13
	s_lshl_b64 s[12:13], s[58:59], 2
	s_add_u32 s12, s7, s12
	s_addc_u32 s13, s24, s13
	s_mov_b64 s[24:25], -1
	s_and_b64 vcc, exec, s[46:47]
	s_cbranch_vccz .LBB0_994
	v_lshl_add_u64 v[8:9], v[168:169], 2, s[12:13]
	v_cmp_gt_i32_e32 vcc, s49, v168
	v_mov_b32_e32 v2, 0
	s_and_saveexec_b64 s[24:25], vcc
	global_load_dword v2, v[8:9], off
	s_or_b64 exec, exec, s[24:25]
	v_cmp_gt_i32_e32 vcc, s49, v194
	v_mov_b32_e32 v3, 0
	s_and_saveexec_b64 s[24:25], vcc
	global_load_dword v3, v[8:9], off offset:256
	s_or_b64 exec, exec, s[24:25]
	v_cmp_gt_i32_e32 vcc, s49, v195
	v_mov_b32_e32 v4, 0
	s_and_saveexec_b64 s[24:25], vcc
	global_load_dword v4, v[8:9], off offset:512
	s_or_b64 exec, exec, s[24:25]
	v_cmp_gt_i32_e32 vcc, s49, v204
	v_mov_b32_e32 v5, 0
	s_and_saveexec_b64 s[24:25], vcc
	global_load_dword v5, v[8:9], off offset:768
	s_or_b64 exec, exec, s[24:25]
	s_waitcnt vmcnt(0)
	v_lshrrev_b32_e32 v2, 1, v2
	v_lshrrev_b32_e32 v3, 1, v3
	v_lshrrev_b32_e32 v4, 1, v4
	v_lshrrev_b32_e32 v5, 1, v5
	s_branch .LBB0_1002
.LBB0_994:
	v_add_u32_e32 v2, s58, v168
	v_add_u32_e32 v3, s58, v194
	v_add_u32_e32 v4, s58, v195
	v_add_u32_e32 v5, s58, v204

; __device__ __forceinline__ unsigned cvt_pk_bf16(float lo, float hi) { f32x2_t v = {lo, hi}; bf16x2_t b = __builtin_convertvector(v, bf16x2_t); return __builtin_bit_cast(unsigned, b); }
;     __device__ __forceinline__ void operator()(const f32x4 (&acc)[2][2][4][2], const Unit& u, int wr, int wc, int fr, int fq) const {
;         const int r0 = wr * 64 + fr, col0 = u.pn * BM + wc * 32 + 8 * fq;
; #pragma unroll
;         for (int ai = 0; ai < 2; ++ai)
; #pragma unroll
;             for (int m = 0; m < 4; ++m) { const int r = r0 + ai * HALF + m * 16;
;                 size_t drow; bool ok = true;
;                 if (moe) { ok = r < u.cnt; drow = ok ? (size_t)(unsigned)list[(size_t)u.e * M + u.aux + r] : 0; } else drow = (size_t)(u.pm * BM + r);
;                 bf16* rowp = Y + drow * D + col0;
; #pragma unroll
;                 for (int bj = 0; bj < 2; ++bj) { const f32x4 v0 = acc[ai][bj][m][0] * osc, v1 = acc[ai][bj][m][1] * osc;
;                     u32x4 w; w.x = cvt_pk_bf16(v0[0], v0[1]); w.y = cvt_pk_bf16(v0[2], v0[3]); w.z = cvt_pk_bf16(v1[0], v1[1]); w.w = cvt_pk_bf16(v1[2], v1[3]);
;                     if (ok) *(u32x4*)(rowp + bj * HALF) = w; } }
;     }
.LBB0_1099:
	s_mov_b64 s[58:59], exec
	v_readlane_b32 s54, v255, 4
	v_readlane_b32 s55, v255, 5
	s_mov_b32 s24, 0x39800000
	s_movk_i32 s26, 0x800
	v_lshl_or_b32 v2, s56, 8, v193
	v_ashrrev_i32_e32 v3, 31, v2
	v_lshl_add_u64 v[2:3], v[2:3], 1, s[54:55]
	s_and_b64 vcc, exec, s[46:47]
	s_cbranch_vccz .Lmy_dn_dense
	s_ashr_i32 s11, s10, 31
	s_ashr_i32 s13, s12, 31
	s_lshl_b64 s[50:51], s[10:11], 18
	s_add_u32 s50, s61, s50
	s_addc_u32 s51, s62, s51
	s_lshl_b64 s[52:53], s[12:13], 2
	s_add_u32 s50, s50, s52
	s_addc_u32 s51, s51, s53
	v_lshl_add_u64 v[4:5], v[168:169], 2, s[50:51]
	v_cmp_gt_i32_e32 vcc, s73, v168
	v_mov_b32_e32 v12, 0
	s_and_saveexec_b64 s[52:53], vcc
	global_load_dword v12, v[4:5], off
	s_mov_b64 exec, s[52:53]
	v_cmp_gt_i32_e32 vcc, s73, v186
	v_mov_b32_e32 v13, 0
	s_and_saveexec_b64 s[52:53], vcc
	global_load_dword v13, v[4:5], off offset:64
	s_mov_b64 exec, s[52:53]
	v_cmp_gt_i32_e32 vcc, s73, v187
	v_mov_b32_e32 v14, 0
	s_and_saveexec_b64 s[52:53], vcc
	global_load_dword v14, v[4:5], off offset:128
	s_mov_b64 exec, s[52:53]
	v_cmp_gt_i32_e32 vcc, s73, v188
	v_mov_b32_e32 v15, 0
	s_and_saveexec_b64 s[52:53], vcc
	global_load_dword v15, v[4:5], off offset:192
	s_mov_b64 exec, s[52:53]
	v_cmp_gt_i32_e32 vcc, s73, v189
	v_mov_b32_e32 v16, 0
	s_and_saveexec_b64 s[52:53], vcc
	global_load_dword v16, v[4:5], off offset:512
	s_mov_b64 exec, s[52:53]
	v_cmp_gt_i32_e32 vcc, s73, v190
	v_mov_b32_e32 v17, 0
	s_and_saveexec_b64 s[52:53], vcc
	global_load_dword v17, v[4:5], off offset:576
	s_mov_b64 exec, s[52:53]
	v_cmp_gt_i32_e32 vcc, s73, v191
	v_mov_b32_e32 v18, 0
	s_and_saveexec_b64 s[52:53], vcc
	global_load_dword v18, v[4:5], off offset:640
	s_mov_b64 exec, s[52:53]
	v_cmp_gt_i32_e32 vcc, s73, v192
	v_mov_b32_e32 v19, 0
	s_and_saveexec_b64 s[52:53], vcc
	global_load_dword v19, v[4:5], off offset:704
	s_mov_b64 exec, s[52:53]
	s_waitcnt vmcnt(0)
	s_branch .Lmy_dn_store
.Lmy_dn_dense:
	v_lshl_add_u32 v12, s2, 8, v168
	v_lshl_add_u32 v13, s2, 8, v186
	v_lshl_add_u32 v14, s2, 8, v187
	v_lshl_add_u32 v15, s2, 8, v188
	v_lshl_add_u32 v16, s2, 8, v189
	v_lshl_add_u32 v17, s2, 8, v190
	v_lshl_add_u32 v18, s2, 8, v191
	v_lshl_add_u32 v19, s2, 8, v192
.Lmy_dn_store:
	v_cmp_gt_i32_e32 vcc, s73, v168
	v_pk_mul_f32 v[4:5], v[160:161], s[24:25] op_sel_hi:[1,0]
	s_and_saveexec_b64 s[52:53], vcc
	v_mad_u64_u32 v[8:9], s[56:57], v12, s26, v[2:3]
	v_pk_mul_f32 v[6:7], v[162:163], s[24:25] op_sel_hi:[1,0]
	v_pk_mul_f32 v[10:11], v[156:157], s[24:25] op_sel_hi:[1,0]
	v_cvt_pk_bf16_f32 v4, v4, v5
	v_cvt_pk_bf16_f32 v5, v6, v7
	v_pk_mul_f32 v[6:7], v[158:159], s[24:25] op_sel_hi:[1,0]
	v_cvt_pk_bf16_f32 v7, v6, v7
	v_cvt_pk_bf16_f32 v6, v10, v11
	global_store_dwordx4 v[8:9], v[4:7], off
	v_pk_mul_f32 v[20:21], v[152:153], s[24:25] op_sel_hi:[1,0]
	v_pk_mul_f32 v[22:23], v[154:155], s[24:25] op_sel_hi:[1,0]
	v_pk_mul_f32 v[10:11], v[148:149], s[24:25] op_sel_hi:[1,0]
	v_cvt_pk_bf16_f32 v20, v20, v21
	v_cvt_pk_bf16_f32 v21, v22, v23
	v_pk_mul_f32 v[22:23], v[150:151], s[24:25] op_sel_hi:[1,0]
	v_cvt_pk_bf16_f32 v23, v22, v23
	v_cvt_pk_bf16_f32 v22, v10, v11
	global_store_dwordx4 v[8:9], v[20:23], off offset:256
	s_mov_b64 exec, s[52:53]
	v_cmp_gt_i32_e32 vcc, s73, v186
	v_pk_mul_f32 v[4:5], v[144:145], s[24:25] op_sel_hi:[1,0]
	s_and_saveexec_b64 s[52:53], vcc
	v_mad_u64_u32 v[8:9], s[56:57], v13, s26, v[2:3]
	v_pk_mul_f32 v[6:7], v[146:147], s[24:25] op_sel_hi:[1,0]
	v_pk_mul_f32 v[10:11], v[140:141], s[24:25] op_sel_hi:[1,0]
	v_cvt_pk_bf16_f32 v4, v4, v5
	v_cvt_pk_bf16_f32 v5, v6, v7
	v_pk_mul_f32 v[6:7], v[142:143], s[24:25] op_sel_hi:[1,0]
	v_cvt_pk_bf16_f32 v7, v6, v7
	v_cvt_pk_bf16_f32 v6, v10, v11
	global_store_dwordx4 v[8:9], v[4:7], off
	v_pk_mul_f32 v[20:21], v[136:137], s[24:25] op_sel_hi:[1,0]
	v_pk_mul_f32 v[22:23], v[138:139], s[24:25] op_sel_hi:[1,0]
	v_pk_mul_f32 v[10:11], v[132:133], s[24:25] op_sel_hi:[1,0]
	v_cvt_pk_bf16_f32 v20, v20, v21
	v_cvt_pk_bf16_f32 v21, v22, v23
	v_pk_mul_f32 v[22:23], v[134:135], s[24:25] op_sel_hi:[1,0]
	v_cvt_pk_bf16_f32 v23, v22, v23
	v_cvt_pk_bf16_f32 v22, v10, v11
	global_store_dwordx4 v[8:9], v[20:23], off offset:256
	s_mov_b64 exec, s[52:53]
	v_cmp_gt_i32_e32 vcc, s73, v187
	v_pk_mul_f32 v[4:5], v[128:129], s[24:25] op_sel_hi:[1,0]
	s_and_saveexec_b64 s[52:53], vcc
	v_mad_u64_u32 v[8:9], s[56:57], v14, s26, v[2:3]
	v_pk_mul_f32 v[6:7], v[130:131], s[24:25] op_sel_hi:[1,0]
	v_pk_mul_f32 v[10:11], v[124:125], s[24:25] op_sel_hi:[1,0]
	v_cvt_pk_bf16_f32 v4, v4, v5
	v_cvt_pk_bf16_f32 v5, v6, v7
	v_pk_mul_f32 v[6:7], v[126:127], s[24:25] op_sel_hi:[1,0]
	v_cvt_pk_bf16_f32 v7, v6, v7
	v_cvt_pk_bf16_f32 v6, v10, v11
	global_store_dwordx4 v[8:9], v[4:7], off
	v_pk_mul_f32 v[20:21], v[120:121], s[24:25] op_sel_hi:[1,0]
	v_pk_mul_f32 v[22:23], v[122:123], s[24:25] op_sel_hi:[1,0]
	v_pk_mul_f32 v[10:11], v[116:117], s[24:25] op_sel_hi:[1,0]
	v_cvt_pk_bf16_f32 v20, v20, v21
	v_cvt_pk_bf16_f32 v21, v22, v23
	v_pk_mul_f32 v[22:23], v[118:119], s[24:25] op_sel_hi:[1,0]
	v_cvt_pk_bf16_f32 v23, v22, v23
; __device__ __forceinline__ unsigned cvt_pk_bf16(float lo, float hi) { f32x2_t v = {lo, hi}; bf16x2_t b = __builtin_convertvector(v, bf16x2_t); return __builtin_bit_cast(unsigned, b); }
;     __device__ __forceinline__ void operator()(const f32x4 (&acc)[2][2][4][2], const Unit& u, int wr, int wc, int fr, int fq) const {
;         const int r0 = wr * 64 + fr, col0 = u.pn * BM + wc * 32 + 8 * fq;
; #pragma unroll
;         for (int ai = 0; ai < 2; ++ai)
; #pragma unroll
;             for (int m = 0; m < 4; ++m) { const int r = r0 + ai * HALF + m * 16;
;                 size_t drow; bool ok = true;
;                 if (moe) { ok = r < u.cnt; drow = ok ? (size_t)(unsigned)list[(size_t)u.e * M + u.aux + r] : 0; } else drow = (size_t)(u.pm * BM + r);
;                 bf16* rowp = Y + drow * D + col0;
; #pragma unroll
;                 for (int bj = 0; bj < 2; ++bj) { const f32x4 v0 = acc[ai][bj][m][0] * osc, v1 = acc[ai][bj][m][1] * osc;
;                     u32x4 w; w.x = cvt_pk_bf16(v0[0], v0[1]); w.y = cvt_pk_bf16(v0[2], v0[3]); w.z = cvt_pk_bf16(v1[0], v1[1]); w.w = cvt_pk_bf16(v1[2], v1[3]);
;                     if (ok) *(u32x4*)(rowp + bj * HALF) = w; } }
;     }
	v_cvt_pk_bf16_f32 v22, v10, v11
	global_store_dwordx4 v[8:9], v[20:23], off offset:256
	s_mov_b64 exec, s[52:53]
	v_cmp_gt_i32_e32 vcc, s73, v188
	v_pk_mul_f32 v[4:5], v[112:113], s[24:25] op_sel_hi:[1,0]
	s_and_saveexec_b64 s[52:53], vcc
	v_mad_u64_u32 v[8:9], s[56:57], v15, s26, v[2:3]
	v_pk_mul_f32 v[6:7], v[114:115], s[24:25] op_sel_hi:[1,0]
	v_pk_mul_f32 v[10:11], v[108:109], s[24:25] op_sel_hi:[1,0]
	v_cvt_pk_bf16_f32 v4, v4, v5
	v_cvt_pk_bf16_f32 v5, v6, v7
	v_pk_mul_f32 v[6:7], v[110:111], s[24:25] op_sel_hi:[1,0]
	v_cvt_pk_bf16_f32 v7, v6, v7
	v_cvt_pk_bf16_f32 v6, v10, v11
	global_store_dwordx4 v[8:9], v[4:7], off
	v_pk_mul_f32 v[20:21], v[104:105], s[24:25] op_sel_hi:[1,0]
	v_pk_mul_f32 v[22:23], v[106:107], s[24:25] op_sel_hi:[1,0]
	v_pk_mul_f32 v[10:11], v[100:101], s[24:25] op_sel_hi:[1,0]
	v_cvt_pk_bf16_f32 v20, v20, v21
	v_cvt_pk_bf16_f32 v21, v22, v23
	v_pk_mul_f32 v[22:23], v[102:103], s[24:25] op_sel_hi:[1,0]
	v_cvt_pk_bf16_f32 v23, v22, v23
	v_cvt_pk_bf16_f32 v22, v10, v11
	global_store_dwordx4 v[8:9], v[20:23], off offset:256
	s_mov_b64 exec, s[52:53]
	v_cmp_gt_i32_e32 vcc, s73, v189
	v_pk_mul_f32 v[4:5], v[96:97], s[24:25] op_sel_hi:[1,0]
	s_and_saveexec_b64 s[52:53], vcc
	v_mad_u64_u32 v[8:9], s[56:57], v16, s26, v[2:3]
	v_pk_mul_f32 v[6:7], v[98:99], s[24:25] op_sel_hi:[1,0]
	v_pk_mul_f32 v[10:11], v[92:93], s[24:25] op_sel_hi:[1,0]
	v_cvt_pk_bf16_f32 v4, v4, v5
	v_cvt_pk_bf16_f32 v5, v6, v7
	v_pk_mul_f32 v[6:7], v[94:95], s[24:25] op_sel_hi:[1,0]
	v_cvt_pk_bf16_f32 v7, v6, v7
	v_cvt_pk_bf16_f32 v6, v10, v11
	global_store_dwordx4 v[8:9], v[4:7], off
	v_pk_mul_f32 v[20:21], v[88:89], s[24:25] op_sel_hi:[1,0]
	v_pk_mul_f32 v[22:23], v[90:91], s[24:25] op_sel_hi:[1,0]
	v_pk_mul_f32 v[10:11], v[84:85], s[24:25] op_sel_hi:[1,0]
	v_cvt_pk_bf16_f32 v20, v20, v21
	v_cvt_pk_bf16_f32 v21, v22, v23
	v_pk_mul_f32 v[22:23], v[86:87], s[24:25] op_sel_hi:[1,0]
	v_cvt_pk_bf16_f32 v23, v22, v23
	v_cvt_pk_bf16_f32 v22, v10, v11
	global_store_dwordx4 v[8:9], v[20:23], off offset:256
	s_mov_b64 exec, s[52:53]
	v_cmp_gt_i32_e32 vcc, s73, v190
	v_pk_mul_f32 v[4:5], v[80:81], s[24:25] op_sel_hi:[1,0]
	s_and_saveexec_b64 s[52:53], vcc
	v_mad_u64_u32 v[8:9], s[56:57], v17, s26, v[2:3]
	v_pk_mul_f32 v[6:7], v[82:83], s[24:25] op_sel_hi:[1,0]
	v_pk_mul_f32 v[10:11], v[76:77], s[24:25] op_sel_hi:[1,0]
	v_cvt_pk_bf16_f32 v4, v4, v5
	v_cvt_pk_bf16_f32 v5, v6, v7
	v_pk_mul_f32 v[6:7], v[78:79], s[24:25] op_sel_hi:[1,0]
	v_cvt_pk_bf16_f32 v7, v6, v7
	v_cvt_pk_bf16_f32 v6, v10, v11
	global_store_dwordx4 v[8:9], v[4:7], off
	v_pk_mul_f32 v[20:21], v[72:73], s[24:25] op_sel_hi:[1,0]
	v_pk_mul_f32 v[22:23], v[74:75], s[24:25] op_sel_hi:[1,0]
	v_pk_mul_f32 v[10:11], v[68:69], s[24:25] op_sel_hi:[1,0]
	v_cvt_pk_bf16_f32 v20, v20, v21
	v_cvt_pk_bf16_f32 v21, v22, v23
	v_pk_mul_f32 v[22:23], v[70:71], s[24:25] op_sel_hi:[1,0]
	v_cvt_pk_bf16_f32 v23, v22, v23
	v_cvt_pk_bf16_f32 v22, v10, v11
	global_store_dwordx4 v[8:9], v[20:23], off offset:256
	s_mov_b64 exec, s[52:53]
	v_cmp_gt_i32_e32 vcc, s73, v191
	v_pk_mul_f32 v[4:5], v[62:63], s[24:25] op_sel_hi:[1,0]
	s_and_saveexec_b64 s[52:53], vcc
	v_mad_u64_u32 v[8:9], s[56:57], v18, s26, v[2:3]
	v_pk_mul_f32 v[6:7], v[64:65], s[24:25] op_sel_hi:[1,0]
	v_pk_mul_f32 v[10:11], v[58:59], s[24:25] op_sel_hi:[1,0]
	v_cvt_pk_bf16_f32 v4, v4, v5
	v_cvt_pk_bf16_f32 v5, v6, v7
	v_pk_mul_f32 v[6:7], v[60:61], s[24:25] op_sel_hi:[1,0]
	v_cvt_pk_bf16_f32 v7, v6, v7
	v_cvt_pk_bf16_f32 v6, v10, v11
	global_store_dwordx4 v[8:9], v[4:7], off
	v_pk_mul_f32 v[20:21], v[54:55], s[24:25] op_sel_hi:[1,0]
	v_pk_mul_f32 v[22:23], v[56:57], s[24:25] op_sel_hi:[1,0]
	v_pk_mul_f32 v[10:11], v[50:51], s[24:25] op_sel_hi:[1,0]
	v_cvt_pk_bf16_f32 v20, v20, v21
	v_cvt_pk_bf16_f32 v21, v22, v23
	v_pk_mul_f32 v[22:23], v[52:53], s[24:25] op_sel_hi:[1,0]
	v_cvt_pk_bf16_f32 v23, v22, v23
	v_cvt_pk_bf16_f32 v22, v10, v11
	global_store_dwordx4 v[8:9], v[20:23], off offset:256
	s_mov_b64 exec, s[52:53]
	v_cmp_gt_i32_e32 vcc, s73, v192
	v_pk_mul_f32 v[4:5], v[46:47], s[24:25] op_sel_hi:[1,0]
	s_and_saveexec_b64 s[52:53], vcc
	v_mad_u64_u32 v[8:9], s[56:57], v19, s26, v[2:3]
	v_pk_mul_f32 v[6:7], v[48:49], s[24:25] op_sel_hi:[1,0]
	v_pk_mul_f32 v[10:11], v[42:43], s[24:25] op_sel_hi:[1,0]
	v_cvt_pk_bf16_f32 v4, v4, v5
	v_cvt_pk_bf16_f32 v5, v6, v7
	v_pk_mul_f32 v[6:7], v[44:45], s[24:25] op_sel_hi:[1,0]
	v_cvt_pk_bf16_f32 v7, v6, v7
	v_cvt_pk_bf16_f32 v6, v10, v11
	global_store_dwordx4 v[8:9], v[4:7], off
	v_pk_mul_f32 v[20:21], v[38:39], s[24:25] op_sel_hi:[1,0]
	v_pk_mul_f32 v[22:23], v[40:41], s[24:25] op_sel_hi:[1,0]
	v_pk_mul_f32 v[10:11], v[34:35], s[24:25] op_sel_hi:[1,0]
	v_cvt_pk_bf16_f32 v20, v20, v21
	v_cvt_pk_bf16_f32 v21, v22, v23
	v_pk_mul_f32 v[22:23], v[36:37], s[24:25] op_sel_hi:[1,0]
	v_cvt_pk_bf16_f32 v23, v22, v23
	v_cvt_pk_bf16_f32 v22, v10, v11
	global_store_dwordx4 v[8:9], v[20:23], off offset:256
	s_mov_b64 exec, s[52:53]
	s_mov_b64 exec, s[58:59]
	s_and_b64 vcc, exec, s[36:37]
	s_mov_b64 s[10:11], -1
	s_cbranch_vccnz .LBB0_1082
